# MLP-up: row statistics of the fast epilogue path loaded during the unit's first K-iteration into spare VGPRs; first two DMA waits of a unit count them and the previous epilogue's 16 stores (vmcnt 16/3
# baseline (speedup 1.0000x reference)
.LBB0_707:
	s_ashr_i32 s45, s44, 31
	s_lshl_b64 s[46:47], s[44:45], 20
	s_add_u32 s46, s80, s46
	s_addc_u32 s47, s81, s47
	s_and_b64 s[48:49], s[38:39], exec
	s_cselect_b32 s41, s47, s87
	s_cselect_b32 s45, s46, s86
	s_ashr_i32 s43, s42, 31
	s_lshl_b64 s[48:49], s[42:43], 20
	s_add_u32 s48, s56, s48
	s_addc_u32 s49, s55, s49
	s_and_b64 s[64:65], s[38:39], exec
	s_cselect_b32 s43, s49, s9
	s_cselect_b32 s63, s48, s8
	s_add_u32 s86, s86, 0x80080
	s_addc_u32 s87, s87, 0
	s_add_u32 s64, s8, 0x100
	v_mov_b32_e32 v2, 0
	s_addc_u32 s65, s9, 0
	s_mov_b32 s66, -2
	v_mov_b32_e32 v3, v2
	v_mov_b32_e32 v4, v2
	v_mov_b32_e32 v5, v2
	v_mov_b32_e32 v6, v2
	v_mov_b32_e32 v7, v2
	v_mov_b32_e32 v8, v2
	v_mov_b32_e32 v9, v2
	v_mov_b32_e32 v18, v2
	v_mov_b32_e32 v19, v2
	v_mov_b32_e32 v20, v2
	v_mov_b32_e32 v21, v2
	v_mov_b32_e32 v22, v2
	v_mov_b32_e32 v23, v2
	v_mov_b32_e32 v24, v2
	v_mov_b32_e32 v25, v2
	v_mov_b32_e32 v34, v2
	v_mov_b32_e32 v35, v2
	v_mov_b32_e32 v36, v2
	v_mov_b32_e32 v37, v2
	v_mov_b32_e32 v38, v2
	v_mov_b32_e32 v39, v2
	v_mov_b32_e32 v40, v2
	v_mov_b32_e32 v41, v2
	v_mov_b32_e32 v50, v2
	v_mov_b32_e32 v51, v2
	v_mov_b32_e32 v52, v2
	v_mov_b32_e32 v53, v2
	v_mov_b32_e32 v54, v2
	v_mov_b32_e32 v55, v2
	v_mov_b32_e32 v56, v2
	v_mov_b32_e32 v57, v2
	v_mov_b32_e32 v10, v2
	v_mov_b32_e32 v11, v2
	v_mov_b32_e32 v12, v2
	v_mov_b32_e32 v13, v2
	v_mov_b32_e32 v14, v2
	v_mov_b32_e32 v15, v2
	v_mov_b32_e32 v16, v2
	v_mov_b32_e32 v17, v2
	v_mov_b32_e32 v26, v2
	v_mov_b32_e32 v27, v2
	v_mov_b32_e32 v28, v2
	v_mov_b32_e32 v29, v2
	v_mov_b32_e32 v30, v2
	v_mov_b32_e32 v31, v2
	v_mov_b32_e32 v32, v2
	v_mov_b32_e32 v33, v2
	v_mov_b32_e32 v42, v2
	v_mov_b32_e32 v43, v2
	v_mov_b32_e32 v44, v2
	v_mov_b32_e32 v45, v2
	v_mov_b32_e32 v46, v2
	v_mov_b32_e32 v47, v2
	v_mov_b32_e32 v48, v2
	v_mov_b32_e32 v49, v2
	v_mov_b32_e32 v58, v2
	v_mov_b32_e32 v59, v2
	v_mov_b32_e32 v60, v2
	v_mov_b32_e32 v61, v2
	v_mov_b32_e32 v62, v2
	v_mov_b32_e32 v63, v2
	v_mov_b32_e32 v64, v2
	v_mov_b32_e32 v65, v2
	v_mov_b32_e32 v66, v2
	v_mov_b32_e32 v67, v2
	v_mov_b32_e32 v68, v2
	v_mov_b32_e32 v69, v2
	v_mov_b32_e32 v70, v2
	v_mov_b32_e32 v71, v2
	v_mov_b32_e32 v72, v2
	v_mov_b32_e32 v73, v2
	v_mov_b32_e32 v82, v2
	v_mov_b32_e32 v83, v2
	v_mov_b32_e32 v84, v2
	v_mov_b32_e32 v85, v2
	v_mov_b32_e32 v86, v2
	v_mov_b32_e32 v87, v2
	v_mov_b32_e32 v88, v2
	v_mov_b32_e32 v89, v2
	v_mov_b32_e32 v98, v2
	v_mov_b32_e32 v99, v2
	v_mov_b32_e32 v100, v2
	v_mov_b32_e32 v101, v2
	v_mov_b32_e32 v102, v2
	v_mov_b32_e32 v103, v2
	v_mov_b32_e32 v104, v2
	v_mov_b32_e32 v105, v2
	v_mov_b32_e32 v120, v2
	v_mov_b32_e32 v121, v2
	v_mov_b32_e32 v122, v2
	v_mov_b32_e32 v123, v2
	v_mov_b32_e32 v124, v2
	v_mov_b32_e32 v125, v2
	v_mov_b32_e32 v126, v2
	v_mov_b32_e32 v127, v2
	v_mov_b32_e32 v74, v2
	v_mov_b32_e32 v75, v2
	v_mov_b32_e32 v76, v2
	v_mov_b32_e32 v77, v2
	v_mov_b32_e32 v78, v2
	v_mov_b32_e32 v79, v2
	v_mov_b32_e32 v80, v2
	v_mov_b32_e32 v81, v2
	v_mov_b32_e32 v90, v2
	v_mov_b32_e32 v91, v2
	v_mov_b32_e32 v92, v2
	v_mov_b32_e32 v93, v2
	v_mov_b32_e32 v94, v2
	v_mov_b32_e32 v95, v2
	v_mov_b32_e32 v96, v2
	v_mov_b32_e32 v97, v2
	v_mov_b32_e32 v106, v2
	v_mov_b32_e32 v107, v2
	v_mov_b32_e32 v108, v2
	v_mov_b32_e32 v109, v2
	v_mov_b32_e32 v116, v2
	v_mov_b32_e32 v117, v2
	v_mov_b32_e32 v118, v2
	v_mov_b32_e32 v119, v2
	v_mov_b32_e32 v128, v2
	v_mov_b32_e32 v129, v2
	v_mov_b32_e32 v130, v2
	v_mov_b32_e32 v131, v2
	v_mov_b32_e32 v132, v2
	v_mov_b32_e32 v133, v2
	v_mov_b32_e32 v134, v2
	v_mov_b32_e32 v135, v2
	s_mov_b32 s98, 0
	s_cmp_lt_i32 s84, 32
	s_cbranch_scc0 .Lmy_pre_done
	v_lshl_add_u32 v251, s84, 8, v1
	v_lshlrev_b32_e32 v251, 2, v251
	s_cmp_eq_u32 s62, 1
	s_cselect_b32 s98, 1, 2
.Lmy_pre_done:
.LBB0_708:
	s_add_u32 s8, s86, 0xfff80080
	s_addc_u32 s9, s87, -1
	s_add_i32 s67, 0, 0x10000
	s_cmp_eq_u32 s66, 28
	s_cselect_b32 s93, s41, s9
	s_cselect_b32 s92, s45, s8
	v_add_u32_e32 v150, s67, v152
	s_cselect_b32 s9, s43, s65
	s_cselect_b32 s8, s63, s64
	s_add_i32 s70, 0, 0x14000
	ds_read_b128 v[146:149], v150
	ds_read_b128 v[156:159], v150 offset:1024
	ds_read_b128 v[160:163], v150 offset:2048
	ds_read_b128 v[170:173], v150 offset:3072
	v_add_u32_e32 v150, s70, v152
	ds_read_b128 v[184:187], v150
	ds_read_b128 v[188:191], v150 offset:1024
	ds_read_b128 v[192:195], v150 offset:2048
	ds_read_b128 v[196:199], v150 offset:3072
	v_lshl_add_u64 v[150:151], s[86:87], 0, v[142:143]
	s_add_i32 m0, s57, 0xc000
	ds_read_b128 v[214:217], v154
	ds_read_b128 v[218:221], v154 offset:1024
	ds_read_b128 v[222:225], v154 offset:2048
	ds_read_b128 v[226:229], v154 offset:3072
	ds_read_b128 v[230:233], v154 offset:4096
	ds_read_b128 v[234:237], v154 offset:5120
	ds_read_b128 v[238:241], v154 offset:6144
	ds_read_b128 v[242:245], v154 offset:7168
	global_load_lds_dwordx4 v[150:151], off
	v_lshl_add_u64 v[150:151], s[86:87], 0, v[144:145]
	s_add_i32 m0, s57, 0xe000
	s_nop 0
	global_load_lds_dwordx4 v[150:151], off
	s_cmp_eq_u32 s98, 0
	s_cbranch_scc1 .Lmy_u1_std
	global_load_dword v167, v251, s[6:7]
	global_load_dword v169, v251, s[6:7] offset:64
	global_load_dword v213, v251, s[6:7] offset:128
	global_load_dword v250, v251, s[6:7] offset:192
	global_load_dword v112, v251, s[6:7] offset:512
	global_load_dword v113, v251, s[6:7] offset:576
	global_load_dword v114, v251, s[6:7] offset:640
	global_load_dword v115, v251, s[6:7] offset:704
	s_cmp_eq_u32 s98, 1
	s_cbranch_scc1 .Lmy_u1_w16
	s_waitcnt vmcnt(32)
	s_branch .Lmy_u1_join
.Lmy_u1_w16:
	s_waitcnt vmcnt(16)
	s_branch .Lmy_u1_join
.Lmy_u1_std:
	s_waitcnt vmcnt(8)
.Lmy_u1_join:
	s_waitcnt lgkmcnt(0)
	s_barrier
	s_setprio 1
	v_mfma_f32_16x16x32_bf16 v[132:135], v[146:149], v[214:217], v[132:135]
	v_mfma_f32_16x16x32_bf16 v[128:131], v[160:163], v[214:217], v[128:131]
	v_mfma_f32_16x16x32_bf16 v[116:119], v[146:149], v[222:225], v[116:119]
	v_mfma_f32_16x16x32_bf16 v[106:109], v[160:163], v[222:225], v[106:109]
	v_mfma_f32_16x16x32_bf16 v[94:97], v[146:149], v[230:233], v[94:97]
	v_mfma_f32_16x16x32_bf16 v[90:93], v[160:163], v[230:233], v[90:93]
	v_mfma_f32_16x16x32_bf16 v[78:81], v[146:149], v[238:241], v[78:81]
	v_mfma_f32_16x16x32_bf16 v[74:77], v[160:163], v[238:241], v[74:77]
	v_mfma_f32_16x16x32_bf16 v[132:135], v[156:159], v[218:221], v[132:135]
	v_mfma_f32_16x16x32_bf16 v[128:131], v[170:173], v[218:221], v[128:131]
	v_mfma_f32_16x16x32_bf16 v[116:119], v[156:159], v[226:229], v[116:119]
	v_mfma_f32_16x16x32_bf16 v[106:109], v[170:173], v[226:229], v[106:109]
	v_mfma_f32_16x16x32_bf16 v[94:97], v[156:159], v[234:237], v[94:97]
	v_mfma_f32_16x16x32_bf16 v[90:93], v[170:173], v[234:237], v[90:93]
	v_mfma_f32_16x16x32_bf16 v[78:81], v[156:159], v[242:245], v[78:81]
	v_mfma_f32_16x16x32_bf16 v[74:77], v[170:173], v[242:245], v[74:77]
	v_mfma_f32_16x16x32_bf16 v[124:127], v[184:187], v[214:217], v[124:127]
	v_mfma_f32_16x16x32_bf16 v[120:123], v[192:195], v[214:217], v[120:123]
	v_mfma_f32_16x16x32_bf16 v[102:105], v[184:187], v[222:225], v[102:105]
	v_mfma_f32_16x16x32_bf16 v[98:101], v[192:195], v[222:225], v[98:101]
	v_mfma_f32_16x16x32_bf16 v[86:89], v[184:187], v[230:233], v[86:89]
	v_mfma_f32_16x16x32_bf16 v[82:85], v[192:195], v[230:233], v[82:85]
	v_mfma_f32_16x16x32_bf16 v[70:73], v[184:187], v[238:241], v[70:73]
	v_mfma_f32_16x16x32_bf16 v[66:69], v[192:195], v[238:241], v[66:69]
	v_mfma_f32_16x16x32_bf16 v[124:127], v[188:191], v[218:221], v[124:127]
	v_mfma_f32_16x16x32_bf16 v[120:123], v[196:199], v[218:221], v[120:123]
	v_mfma_f32_16x16x32_bf16 v[102:105], v[188:191], v[226:229], v[102:105]
	v_mfma_f32_16x16x32_bf16 v[98:101], v[196:199], v[226:229], v[98:101]
	v_mfma_f32_16x16x32_bf16 v[86:89], v[188:191], v[234:237], v[86:89]
	v_mfma_f32_16x16x32_bf16 v[82:85], v[196:199], v[234:237], v[82:85]
	v_mfma_f32_16x16x32_bf16 v[70:73], v[188:191], v[242:245], v[70:73]
	v_mfma_f32_16x16x32_bf16 v[66:69], v[196:199], v[242:245], v[66:69]
	s_setprio 0
	s_barrier
	s_add_i32 s67, s67, s54
	v_lshl_add_u64 v[150:151], s[8:9], 0, v[136:137]
	s_mov_b32 m0, s67
	ds_read_b128 v[214:217], v154 offset:16384
	ds_read_b128 v[218:221], v154 offset:17408
	ds_read_b128 v[222:225], v154 offset:18432
	ds_read_b128 v[226:229], v154 offset:19456
	ds_read_b128 v[230:233], v154 offset:20480
	ds_read_b128 v[234:237], v154 offset:21504
	ds_read_b128 v[238:241], v154 offset:22528
	ds_read_b128 v[242:245], v154 offset:23552
	global_load_lds_dwordx4 v[150:151], off
	s_add_i32 m0, s67, 0x2000
	s_add_u32 s68, s8, 0x80000
	v_lshl_add_u64 v[200:201], s[8:9], 0, v[140:141]
	s_addc_u32 s69, s9, 0
	s_add_i32 s67, s70, s54
	global_load_lds_dwordx4 v[200:201], off
	v_lshl_add_u64 v[206:207], s[68:69], 0, v[136:137]
	s_mov_b32 m0, s67
	v_lshl_add_u64 v[246:247], s[92:93], 0, v[138:139]
	global_load_lds_dwordx4 v[206:207], off
	v_lshl_add_u64 v[206:207], s[68:69], 0, v[140:141]
	s_add_i32 m0, s67, 0x2000
	s_nop 0
	global_load_lds_dwordx4 v[206:207], off
	v_lshl_add_u64 v[206:207], s[92:93], 0, v[110:111]
	s_mov_b32 m0, s57
	s_nop 0
	global_load_lds_dwordx4 v[206:207], off
	s_mov_b32 m0, s58
	s_nop 0
	global_load_lds_dwordx4 v[246:247], off
	s_cmp_eq_u32 s98, 0
	s_cbranch_scc1 .Lmy_u2_std
	s_cmp_eq_u32 s98, 1
	s_mov_b32 s98, 0
	s_cbranch_scc1 .Lmy_u2_w16
	s_waitcnt vmcnt(32)
	s_branch .Lmy_u2_join

.Lmy_u2_join:
	s_waitcnt lgkmcnt(0)
	s_barrier
	s_setprio 1
	v_mfma_f32_16x16x32_bf16 v[62:65], v[146:149], v[214:217], v[62:65]
	v_mfma_f32_16x16x32_bf16 v[58:61], v[160:163], v[214:217], v[58:61]
	v_mfma_f32_16x16x32_bf16 v[46:49], v[146:149], v[222:225], v[46:49]
	v_mfma_f32_16x16x32_bf16 v[42:45], v[160:163], v[222:225], v[42:45]
	v_mfma_f32_16x16x32_bf16 v[30:33], v[146:149], v[230:233], v[30:33]
	v_mfma_f32_16x16x32_bf16 v[26:29], v[160:163], v[230:233], v[26:29]
	v_mfma_f32_16x16x32_bf16 v[14:17], v[146:149], v[238:241], v[14:17]
	v_mfma_f32_16x16x32_bf16 v[10:13], v[160:163], v[238:241], v[10:13]
	v_mfma_f32_16x16x32_bf16 v[62:65], v[156:159], v[218:221], v[62:65]
	v_mfma_f32_16x16x32_bf16 v[58:61], v[170:173], v[218:221], v[58:61]
	v_mfma_f32_16x16x32_bf16 v[46:49], v[156:159], v[226:229], v[46:49]
	v_mfma_f32_16x16x32_bf16 v[42:45], v[170:173], v[226:229], v[42:45]
	v_mfma_f32_16x16x32_bf16 v[30:33], v[156:159], v[234:237], v[30:33]
	v_mfma_f32_16x16x32_bf16 v[26:29], v[170:173], v[234:237], v[26:29]
	v_mfma_f32_16x16x32_bf16 v[14:17], v[156:159], v[242:245], v[14:17]
	v_mfma_f32_16x16x32_bf16 v[10:13], v[170:173], v[242:245], v[10:13]
	v_mfma_f32_16x16x32_bf16 v[54:57], v[184:187], v[214:217], v[54:57]
	v_mfma_f32_16x16x32_bf16 v[50:53], v[192:195], v[214:217], v[50:53]
	v_mfma_f32_16x16x32_bf16 v[38:41], v[184:187], v[222:225], v[38:41]
	v_mfma_f32_16x16x32_bf16 v[34:37], v[192:195], v[222:225], v[34:37]
	v_mfma_f32_16x16x32_bf16 v[22:25], v[184:187], v[230:233], v[22:25]
	v_mfma_f32_16x16x32_bf16 v[18:21], v[192:195], v[230:233], v[18:21]
	v_mfma_f32_16x16x32_bf16 v[6:9], v[184:187], v[238:241], v[6:9]
	v_mfma_f32_16x16x32_bf16 v[2:5], v[192:195], v[238:241], v[2:5]
	v_mfma_f32_16x16x32_bf16 v[54:57], v[188:191], v[218:221], v[54:57]
	v_mfma_f32_16x16x32_bf16 v[50:53], v[196:199], v[218:221], v[50:53]
	v_mfma_f32_16x16x32_bf16 v[38:41], v[188:191], v[226:229], v[38:41]
	v_mfma_f32_16x16x32_bf16 v[34:37], v[196:199], v[226:229], v[34:37]
	v_mfma_f32_16x16x32_bf16 v[22:25], v[188:191], v[234:237], v[22:25]
	v_mfma_f32_16x16x32_bf16 v[18:21], v[196:199], v[234:237], v[18:21]
	v_mfma_f32_16x16x32_bf16 v[6:9], v[188:191], v[242:245], v[6:9]
	v_mfma_f32_16x16x32_bf16 v[2:5], v[196:199], v[242:245], v[2:5]
	s_setprio 0
	s_barrier
	s_add_i32 s67, 0, 0x18000
	v_add_u32_e32 v155, s67, v152
	s_add_i32 s70, 0, 0x1c000
	ds_read_b128 v[146:149], v155
	ds_read_b128 v[156:159], v155 offset:1024
	ds_read_b128 v[160:163], v155 offset:2048
	ds_read_b128 v[170:173], v155 offset:3072
	v_add_u32_e32 v155, s70, v152
	ds_read_b128 v[184:187], v155
	ds_read_b128 v[188:191], v155 offset:1024
	ds_read_b128 v[192:195], v155 offset:2048
	ds_read_b128 v[196:199], v155 offset:3072
	s_add_u32 s68, s92, 0x80000
	s_addc_u32 s69, s93, 0
	s_mov_b32 m0, s59
	v_lshl_add_u64 v[248:249], s[68:69], 0, v[110:111]
	ds_read_b128 v[214:217], v154 offset:32768
	ds_read_b128 v[218:221], v154 offset:33792
	ds_read_b128 v[222:225], v154 offset:34816
	ds_read_b128 v[226:229], v154 offset:35840
	ds_read_b128 v[230:233], v154 offset:36864
	ds_read_b128 v[234:237], v154 offset:37888
	ds_read_b128 v[238:241], v154 offset:38912
	ds_read_b128 v[242:245], v154 offset:39936
	global_load_lds_dwordx4 v[248:249], off
	v_lshl_add_u64 v[248:249], s[68:69], 0, v[138:139]
	s_mov_b32 m0, s60
	s_nop 0
	global_load_lds_dwordx4 v[248:249], off
	s_waitcnt vmcnt(8)
	s_waitcnt lgkmcnt(0)
	s_barrier
	s_setprio 1
	v_mfma_f32_16x16x32_bf16 v[132:135], v[146:149], v[214:217], v[132:135]
	v_mfma_f32_16x16x32_bf16 v[128:131], v[160:163], v[214:217], v[128:131]
	v_mfma_f32_16x16x32_bf16 v[116:119], v[146:149], v[222:225], v[116:119]
	v_mfma_f32_16x16x32_bf16 v[106:109], v[160:163], v[222:225], v[106:109]
	v_mfma_f32_16x16x32_bf16 v[94:97], v[146:149], v[230:233], v[94:97]
	v_mfma_f32_16x16x32_bf16 v[90:93], v[160:163], v[230:233], v[90:93]
	v_mfma_f32_16x16x32_bf16 v[78:81], v[146:149], v[238:241], v[78:81]
	v_mfma_f32_16x16x32_bf16 v[74:77], v[160:163], v[238:241], v[74:77]
	v_mfma_f32_16x16x32_bf16 v[132:135], v[156:159], v[218:221], v[132:135]
	v_mfma_f32_16x16x32_bf16 v[128:131], v[170:173], v[218:221], v[128:131]
	v_mfma_f32_16x16x32_bf16 v[116:119], v[156:159], v[226:229], v[116:119]
	v_mfma_f32_16x16x32_bf16 v[106:109], v[170:173], v[226:229], v[106:109]
	v_mfma_f32_16x16x32_bf16 v[94:97], v[156:159], v[234:237], v[94:97]
	v_mfma_f32_16x16x32_bf16 v[90:93], v[170:173], v[234:237], v[90:93]
	v_mfma_f32_16x16x32_bf16 v[78:81], v[156:159], v[242:245], v[78:81]
	v_mfma_f32_16x16x32_bf16 v[74:77], v[170:173], v[242:245], v[74:77]
	v_mfma_f32_16x16x32_bf16 v[124:127], v[184:187], v[214:217], v[124:127]
	v_mfma_f32_16x16x32_bf16 v[120:123], v[192:195], v[214:217], v[120:123]
	v_mfma_f32_16x16x32_bf16 v[102:105], v[184:187], v[222:225], v[102:105]
	v_mfma_f32_16x16x32_bf16 v[98:101], v[192:195], v[222:225], v[98:101]
	v_mfma_f32_16x16x32_bf16 v[86:89], v[184:187], v[230:233], v[86:89]
	v_mfma_f32_16x16x32_bf16 v[82:85], v[192:195], v[230:233], v[82:85]
	v_mfma_f32_16x16x32_bf16 v[70:73], v[184:187], v[238:241], v[70:73]
	v_mfma_f32_16x16x32_bf16 v[66:69], v[192:195], v[238:241], v[66:69]
	v_mfma_f32_16x16x32_bf16 v[124:127], v[188:191], v[218:221], v[124:127]
	v_mfma_f32_16x16x32_bf16 v[120:123], v[196:199], v[218:221], v[120:123]
	v_mfma_f32_16x16x32_bf16 v[102:105], v[188:191], v[226:229], v[102:105]
	v_mfma_f32_16x16x32_bf16 v[98:101], v[196:199], v[226:229], v[98:101]
	v_mfma_f32_16x16x32_bf16 v[86:89], v[188:191], v[234:237], v[86:89]
	v_mfma_f32_16x16x32_bf16 v[82:85], v[196:199], v[234:237], v[82:85]
	v_mfma_f32_16x16x32_bf16 v[70:73], v[188:191], v[242:245], v[70:73]
	v_mfma_f32_16x16x32_bf16 v[66:69], v[196:199], v[242:245], v[66:69]
	s_setprio 0
	s_barrier
	s_add_i32 s67, s67, s54
	v_lshl_add_u64 v[150:151], v[150:151], 0, s[26:27]
	s_mov_b32 m0, s67
	ds_read_b128 v[214:217], v154 offset:49152
	ds_read_b128 v[218:221], v154 offset:50176
	ds_read_b128 v[222:225], v154 offset:51200
	ds_read_b128 v[226:229], v154 offset:52224
	ds_read_b128 v[230:233], v154 offset:53248
	ds_read_b128 v[234:237], v154 offset:54272
	ds_read_b128 v[238:241], v154 offset:55296
	ds_read_b128 v[242:245], v154 offset:56320
	global_load_lds_dwordx4 v[150:151], off
	s_add_i32 m0, s67, 0x2000
	s_add_u32 s8, s8, 0x80080
	v_lshl_add_u64 v[150:151], v[200:201], 0, s[26:27]
	s_addc_u32 s9, s9, 0
	s_add_i32 s67, s70, s54
	global_load_lds_dwordx4 v[150:151], off
	v_lshl_add_u64 v[150:151], s[8:9], 0, v[136:137]
	s_mov_b32 m0, s67
	s_nop 0
	global_load_lds_dwordx4 v[150:151], off
	v_lshl_add_u64 v[150:151], s[8:9], 0, v[140:141]
	s_add_i32 m0, s67, 0x2000
	s_nop 0
	global_load_lds_dwordx4 v[150:151], off
	v_lshl_add_u64 v[150:151], v[206:207], 0, s[26:27]
	s_mov_b32 m0, s37
	s_nop 0
	global_load_lds_dwordx4 v[150:151], off
	v_lshl_add_u64 v[150:151], v[246:247], 0, s[26:27]
	s_mov_b32 m0, s61
	s_nop 0
	global_load_lds_dwordx4 v[150:151], off
	s_waitcnt vmcnt(8)
	s_waitcnt lgkmcnt(0)
	s_barrier
	s_setprio 1
	v_mfma_f32_16x16x32_bf16 v[62:65], v[146:149], v[214:217], v[62:65]
	v_mfma_f32_16x16x32_bf16 v[58:61], v[160:163], v[214:217], v[58:61]
	v_mfma_f32_16x16x32_bf16 v[46:49], v[146:149], v[222:225], v[46:49]
	v_mfma_f32_16x16x32_bf16 v[42:45], v[160:163], v[222:225], v[42:45]
	v_mfma_f32_16x16x32_bf16 v[30:33], v[146:149], v[230:233], v[30:33]
	v_mfma_f32_16x16x32_bf16 v[26:29], v[160:163], v[230:233], v[26:29]
	v_mfma_f32_16x16x32_bf16 v[14:17], v[146:149], v[238:241], v[14:17]
	v_mfma_f32_16x16x32_bf16 v[10:13], v[160:163], v[238:241], v[10:13]
	v_mfma_f32_16x16x32_bf16 v[62:65], v[156:159], v[218:221], v[62:65]
	v_mfma_f32_16x16x32_bf16 v[58:61], v[170:173], v[218:221], v[58:61]
	v_mfma_f32_16x16x32_bf16 v[46:49], v[156:159], v[226:229], v[46:49]
	v_mfma_f32_16x16x32_bf16 v[42:45], v[170:173], v[226:229], v[42:45]
	v_mfma_f32_16x16x32_bf16 v[30:33], v[156:159], v[234:237], v[30:33]
	v_mfma_f32_16x16x32_bf16 v[26:29], v[170:173], v[234:237], v[26:29]
	v_mfma_f32_16x16x32_bf16 v[14:17], v[156:159], v[242:245], v[14:17]
	v_mfma_f32_16x16x32_bf16 v[10:13], v[170:173], v[242:245], v[10:13]
	v_mfma_f32_16x16x32_bf16 v[54:57], v[184:187], v[214:217], v[54:57]
	v_mfma_f32_16x16x32_bf16 v[50:53], v[192:195], v[214:217], v[50:53]
	v_mfma_f32_16x16x32_bf16 v[38:41], v[184:187], v[222:225], v[38:41]
	v_mfma_f32_16x16x32_bf16 v[34:37], v[192:195], v[222:225], v[34:37]
	v_mfma_f32_16x16x32_bf16 v[22:25], v[184:187], v[230:233], v[22:25]
	v_mfma_f32_16x16x32_bf16 v[18:21], v[192:195], v[230:233], v[18:21]
	v_mfma_f32_16x16x32_bf16 v[6:9], v[184:187], v[238:241], v[6:9]
	v_mfma_f32_16x16x32_bf16 v[2:5], v[192:195], v[238:241], v[2:5]
	v_mfma_f32_16x16x32_bf16 v[54:57], v[188:191], v[218:221], v[54:57]
	v_mfma_f32_16x16x32_bf16 v[50:53], v[196:199], v[218:221], v[50:53]
	v_mfma_f32_16x16x32_bf16 v[38:41], v[188:191], v[226:229], v[38:41]
	v_mfma_f32_16x16x32_bf16 v[34:37], v[196:199], v[226:229], v[34:37]
	v_mfma_f32_16x16x32_bf16 v[22:25], v[188:191], v[234:237], v[22:25]
	v_mfma_f32_16x16x32_bf16 v[18:21], v[196:199], v[234:237], v[18:21]
	v_mfma_f32_16x16x32_bf16 v[6:9], v[188:191], v[242:245], v[6:9]
	v_mfma_f32_16x16x32_bf16 v[2:5], v[196:199], v[242:245], v[2:5]
	s_setprio 0
	s_barrier
	s_add_i32 s66, s66, 2
	s_add_u32 s86, s86, 0x100
	s_addc_u32 s87, s87, 0
	s_add_u32 s64, s64, 0x100
	s_addc_u32 s65, s65, 0
	s_cmp_gt_u32 s66, 29
	s_cbranch_scc0 .LBB0_708
	s_and_b64 vcc, exec, s[16:17]
	s_cbranch_vccz .LBB0_711
	s_barrier
.LBB0_711:
	v_lshl_add_u32 v146, s84, 8, v1
	s_cmp_lt_i32 s84, 32
	s_cselect_b64 s[8:9], -1, 0
	v_ashrrev_i32_e32 v147, 31, v146
	v_readlane_b32 s64, v255, 12
	s_mov_b64 s[84:85], -1
	s_and_b64 vcc, exec, s[8:9]
	v_lshl_add_u64 v[150:151], v[146:147], 2, s[6:7]
	v_readlane_b32 s65, v255, 13
	s_cbranch_vccz .LBB0_713
	s_waitcnt vmcnt(8)
	v_mov_b32_e32 v214, v167
	v_mov_b32_e32 v215, v169
	v_mov_b32_e32 v216, v213
	v_mov_b32_e32 v217, v250
	v_mov_b32_e32 v218, v112
	v_mov_b32_e32 v219, v113
	v_mov_b32_e32 v220, v114
	v_mov_b32_e32 v221, v115
	v_mov_b32_e32 v112, 0
	v_mov_b32_e32 v113, 0
	v_mov_b32_e32 v114, 0
	v_mov_b32_e32 v115, 0
	v_mov_b32_e32 v155, v214
	s_mov_b64 s[84:85], 0
